# isel top-k histogram: address/zero-test chains of three keys interleaved through separate temporaries instead of one serial v2/vcc chain
# speedup vs baseline: 1.0033x; 1.0003x over previous
.LBB0_479:
	s_cmpk_gt_i32 s29, 0xff
	s_cbranch_scc0 .LBB0_512
	s_mov_b32 s72, s73
	s_mov_b32 s74, s73
	s_mov_b32 s75, s73
	v_mov_b64_e32 v[68:69], s[72:73]
	v_lshl_add_u32 v2, v221, 4, s34
	v_mov_b64_e32 v[70:71], s[74:75]
	ds_write_b128 v2, v[68:71]
	ds_write_b128 v2, v[68:71] offset:1024
	ds_write_b128 v2, v[68:71] offset:2048
	ds_write_b128 v2, v[68:71] offset:3072
	ds_write_b128 v2, v[68:71] offset:4096
	ds_write_b128 v2, v[68:71] offset:5120
	ds_write_b128 v2, v[68:71] offset:6144
	ds_write_b128 v2, v[68:71] offset:7168
	ds_write_b128 v2, v[68:71] offset:8192
	ds_write_b128 v2, v[68:71] offset:9216
	ds_write_b128 v2, v[68:71] offset:10240
	ds_write_b128 v2, v[68:71] offset:11264
	ds_write_b128 v2, v[68:71] offset:12288
	ds_write_b128 v2, v[68:71] offset:13312
	ds_write_b128 v2, v[68:71] offset:14336
	ds_write_b128 v2, v[68:71] offset:15360
	s_and_b64 vcc, exec, s[30:31]
	s_cbranch_vccz .LBB0_482
	s_waitcnt lgkmcnt(14)
	v_cmp_eq_u32_e32 vcc, 0, v4
	v_cmp_eq_u32_e64 s[98:99], 0, v0
	v_cmp_eq_u32_e64 s[100:101], 0, v6
	v_lshrrev_b32_e32 v2, 20, v4
	v_lshrrev_b32_e32 v3, 20, v0
	v_lshrrev_b32_e32 v67, 20, v6
	v_cndmask_b32_e32 v2, v2, v221, vcc
	v_cndmask_b32_e64 v3, v3, v221, s[98:99]
	v_cndmask_b32_e64 v67, v67, v221, s[100:101]
	v_lshl_add_u32 v2, v2, 2, s34
	v_lshl_add_u32 v3, v3, 2, s34
	v_lshl_add_u32 v67, v67, 2, s34
	ds_add_u32 v2, v213
	ds_add_u32 v3, v213
	ds_add_u32 v67, v213
	v_cmp_eq_u32_e32 vcc, 0, v5
	v_cmp_eq_u32_e64 s[98:99], 0, v8
	v_cmp_eq_u32_e64 s[100:101], 0, v7
	v_lshrrev_b32_e32 v2, 20, v5
	v_lshrrev_b32_e32 v3, 20, v8
	v_lshrrev_b32_e32 v67, 20, v7
	v_cndmask_b32_e32 v2, v2, v221, vcc
	v_cndmask_b32_e64 v3, v3, v221, s[98:99]
	v_cndmask_b32_e64 v67, v67, v221, s[100:101]
	v_lshl_add_u32 v2, v2, 2, s34
	v_lshl_add_u32 v3, v3, 2, s34
	v_lshl_add_u32 v67, v67, 2, s34
	ds_add_u32 v2, v213
	ds_add_u32 v3, v213
	ds_add_u32 v67, v213
	v_cmp_eq_u32_e32 vcc, 0, v10
	v_cmp_eq_u32_e64 s[98:99], 0, v9
	v_lshrrev_b32_e32 v2, 20, v10
	v_lshrrev_b32_e32 v3, 20, v9
	v_cndmask_b32_e32 v2, v2, v221, vcc
	v_cndmask_b32_e64 v3, v3, v221, s[98:99]
	v_lshl_add_u32 v2, v2, 2, s34
	v_lshl_add_u32 v3, v3, 2, s34
	ds_add_u32 v2, v213
	ds_add_u32 v3, v213
.LBB0_482:
	v_cndmask_b32_e64 v2, 0, 1, s[4:5]
	v_cmp_ne_u32_e64 s[0:1], 1, v2
	s_andn2_b64 vcc, exec, s[4:5]
	s_cbranch_vccnz .LBB0_484
	s_waitcnt lgkmcnt(14)
	v_cmp_eq_u32_e32 vcc, 0, v12
	v_cmp_eq_u32_e64 s[98:99], 0, v11
	v_cmp_eq_u32_e64 s[100:101], 0, v14
	v_lshrrev_b32_e32 v2, 20, v12
	v_lshrrev_b32_e32 v3, 20, v11
	v_lshrrev_b32_e32 v67, 20, v14
	v_cndmask_b32_e32 v2, v2, v221, vcc
	v_cndmask_b32_e64 v3, v3, v221, s[98:99]
	v_cndmask_b32_e64 v67, v67, v221, s[100:101]
	v_lshl_add_u32 v2, v2, 2, s34
	v_lshl_add_u32 v3, v3, 2, s34
	v_lshl_add_u32 v67, v67, 2, s34
	ds_add_u32 v2, v213
	ds_add_u32 v3, v213
	ds_add_u32 v67, v213
	v_cmp_eq_u32_e32 vcc, 0, v13
	v_cmp_eq_u32_e64 s[98:99], 0, v16
	v_cmp_eq_u32_e64 s[100:101], 0, v15
	v_lshrrev_b32_e32 v2, 20, v13
	v_lshrrev_b32_e32 v3, 20, v16
	v_lshrrev_b32_e32 v67, 20, v15
	v_cndmask_b32_e32 v2, v2, v221, vcc
	v_cndmask_b32_e64 v3, v3, v221, s[98:99]
	v_cndmask_b32_e64 v67, v67, v221, s[100:101]
	v_lshl_add_u32 v2, v2, 2, s34
	v_lshl_add_u32 v3, v3, 2, s34
	v_lshl_add_u32 v67, v67, 2, s34
	ds_add_u32 v2, v213
	ds_add_u32 v3, v213
	ds_add_u32 v67, v213
	v_cmp_eq_u32_e32 vcc, 0, v18
	v_cmp_eq_u32_e64 s[98:99], 0, v17
	v_lshrrev_b32_e32 v2, 20, v18
	v_lshrrev_b32_e32 v3, 20, v17
	v_cndmask_b32_e32 v2, v2, v221, vcc
	v_cndmask_b32_e64 v3, v3, v221, s[98:99]
	v_lshl_add_u32 v2, v2, 2, s34
	v_lshl_add_u32 v3, v3, 2, s34
	ds_add_u32 v2, v213
	ds_add_u32 v3, v213

.LBB0_490:
	s_waitcnt lgkmcnt(14)
	v_cmp_eq_u32_e32 vcc, 0, v60
	v_cmp_eq_u32_e64 s[98:99], 0, v59
	v_cmp_eq_u32_e64 s[100:101], 0, v62
	v_lshrrev_b32_e32 v2, 20, v60
	v_lshrrev_b32_e32 v3, 20, v59
	v_lshrrev_b32_e32 v67, 20, v62
	v_cndmask_b32_e32 v2, v2, v221, vcc
	v_cndmask_b32_e64 v3, v3, v221, s[98:99]
	v_cndmask_b32_e64 v67, v67, v221, s[100:101]
	v_lshl_add_u32 v2, v2, 2, s34
	v_lshl_add_u32 v3, v3, 2, s34
	v_lshl_add_u32 v67, v67, 2, s34
	ds_add_u32 v2, v213
	ds_add_u32 v3, v213
	ds_add_u32 v67, v213
	v_cmp_eq_u32_e32 vcc, 0, v61
	v_cmp_eq_u32_e64 s[98:99], 0, v64
	v_cmp_eq_u32_e64 s[100:101], 0, v63
	v_lshrrev_b32_e32 v2, 20, v61
	v_lshrrev_b32_e32 v3, 20, v64
	v_lshrrev_b32_e32 v67, 20, v63
	v_cndmask_b32_e32 v2, v2, v221, vcc
	v_cndmask_b32_e64 v3, v3, v221, s[98:99]
	v_cndmask_b32_e64 v67, v67, v221, s[100:101]
	v_lshl_add_u32 v2, v2, 2, s34
	v_lshl_add_u32 v3, v3, 2, s34
	v_lshl_add_u32 v67, v67, 2, s34
	ds_add_u32 v2, v213
	ds_add_u32 v3, v213
	ds_add_u32 v67, v213
	v_cmp_eq_u32_e32 vcc, 0, v66
	v_cmp_eq_u32_e64 s[98:99], 0, v65
	v_lshrrev_b32_e32 v2, 20, v66
	v_lshrrev_b32_e32 v3, 20, v65
	v_cndmask_b32_e32 v2, v2, v221, vcc
	v_cndmask_b32_e64 v3, v3, v221, s[98:99]
	v_lshl_add_u32 v2, v2, 2, s34
	v_lshl_add_u32 v3, v3, 2, s34
	ds_add_u32 v2, v213
	ds_add_u32 v3, v213

.LBB0_515:
	s_waitcnt lgkmcnt(14)
	v_cmp_eq_u32_e32 vcc, 0, v20
	v_cmp_eq_u32_e64 s[98:99], 0, v19
	v_cmp_eq_u32_e64 s[100:101], 0, v22
	v_lshrrev_b32_e32 v2, 20, v20
	v_lshrrev_b32_e32 v3, 20, v19
	v_lshrrev_b32_e32 v67, 20, v22
	v_cndmask_b32_e32 v2, v2, v221, vcc
	v_cndmask_b32_e64 v3, v3, v221, s[98:99]
	v_cndmask_b32_e64 v67, v67, v221, s[100:101]
	v_lshl_add_u32 v2, v2, 2, s34
	v_lshl_add_u32 v3, v3, 2, s34
	v_lshl_add_u32 v67, v67, 2, s34
	ds_add_u32 v2, v213
	ds_add_u32 v3, v213
	ds_add_u32 v67, v213
	v_cmp_eq_u32_e32 vcc, 0, v21
	v_cmp_eq_u32_e64 s[98:99], 0, v24
	v_cmp_eq_u32_e64 s[100:101], 0, v23
	v_lshrrev_b32_e32 v2, 20, v21
	v_lshrrev_b32_e32 v3, 20, v24
	v_lshrrev_b32_e32 v67, 20, v23
	v_cndmask_b32_e32 v2, v2, v221, vcc
	v_cndmask_b32_e64 v3, v3, v221, s[98:99]
	v_cndmask_b32_e64 v67, v67, v221, s[100:101]
	v_lshl_add_u32 v2, v2, 2, s34
	v_lshl_add_u32 v3, v3, 2, s34
	v_lshl_add_u32 v67, v67, 2, s34
	ds_add_u32 v2, v213
	ds_add_u32 v3, v213
	ds_add_u32 v67, v213
	v_cmp_eq_u32_e32 vcc, 0, v26
	v_cmp_eq_u32_e64 s[98:99], 0, v25
	v_lshrrev_b32_e32 v2, 20, v26
	v_lshrrev_b32_e32 v3, 20, v25
	v_cndmask_b32_e32 v2, v2, v221, vcc
	v_cndmask_b32_e64 v3, v3, v221, s[98:99]
	v_lshl_add_u32 v2, v2, 2, s34
	v_lshl_add_u32 v3, v3, 2, s34
	ds_add_u32 v2, v213
	ds_add_u32 v3, v213
	v_cndmask_b32_e64 v2, 0, 1, s[6:7]
	v_cmp_ne_u32_e64 s[4:5], 1, v2
	s_andn2_b64 vcc, exec, s[6:7]
	s_cbranch_vccnz .LBB0_486
.LBB0_516:
	s_waitcnt lgkmcnt(14)
	v_cmp_eq_u32_e32 vcc, 0, v28
	v_cmp_eq_u32_e64 s[98:99], 0, v27
	v_cmp_eq_u32_e64 s[100:101], 0, v30
	v_lshrrev_b32_e32 v2, 20, v28
	v_lshrrev_b32_e32 v3, 20, v27
	v_lshrrev_b32_e32 v67, 20, v30
	v_cndmask_b32_e32 v2, v2, v221, vcc
	v_cndmask_b32_e64 v3, v3, v221, s[98:99]
	v_cndmask_b32_e64 v67, v67, v221, s[100:101]
	v_lshl_add_u32 v2, v2, 2, s34
	v_lshl_add_u32 v3, v3, 2, s34
	v_lshl_add_u32 v67, v67, 2, s34
	ds_add_u32 v2, v213
	ds_add_u32 v3, v213
	ds_add_u32 v67, v213
	v_cmp_eq_u32_e32 vcc, 0, v29
	v_cmp_eq_u32_e64 s[98:99], 0, v32
	v_cmp_eq_u32_e64 s[100:101], 0, v31
	v_lshrrev_b32_e32 v2, 20, v29
	v_lshrrev_b32_e32 v3, 20, v32
	v_lshrrev_b32_e32 v67, 20, v31
	v_cndmask_b32_e32 v2, v2, v221, vcc
	v_cndmask_b32_e64 v3, v3, v221, s[98:99]
	v_cndmask_b32_e64 v67, v67, v221, s[100:101]
	v_lshl_add_u32 v2, v2, 2, s34
	v_lshl_add_u32 v3, v3, 2, s34
	v_lshl_add_u32 v67, v67, 2, s34
	ds_add_u32 v2, v213
	ds_add_u32 v3, v213
	ds_add_u32 v67, v213
	v_cmp_eq_u32_e32 vcc, 0, v34
	v_cmp_eq_u32_e64 s[98:99], 0, v33
	v_lshrrev_b32_e32 v2, 20, v34
	v_lshrrev_b32_e32 v3, 20, v33
	v_cndmask_b32_e32 v2, v2, v221, vcc
	v_cndmask_b32_e64 v3, v3, v221, s[98:99]
	v_lshl_add_u32 v2, v2, 2, s34
	v_lshl_add_u32 v3, v3, 2, s34
	ds_add_u32 v2, v213
	ds_add_u32 v3, v213
	v_cndmask_b32_e64 v2, 0, 1, s[8:9]
	v_cmp_ne_u32_e64 s[6:7], 1, v2
	s_andn2_b64 vcc, exec, s[8:9]
	s_cbranch_vccnz .LBB0_487
.LBB0_517:
	s_waitcnt lgkmcnt(14)
	v_cmp_eq_u32_e32 vcc, 0, v36
	v_cmp_eq_u32_e64 s[98:99], 0, v35
	v_cmp_eq_u32_e64 s[100:101], 0, v38
	v_lshrrev_b32_e32 v2, 20, v36
	v_lshrrev_b32_e32 v3, 20, v35
	v_lshrrev_b32_e32 v67, 20, v38
	v_cndmask_b32_e32 v2, v2, v221, vcc
	v_cndmask_b32_e64 v3, v3, v221, s[98:99]
	v_cndmask_b32_e64 v67, v67, v221, s[100:101]
	v_lshl_add_u32 v2, v2, 2, s34
	v_lshl_add_u32 v3, v3, 2, s34
	v_lshl_add_u32 v67, v67, 2, s34
	ds_add_u32 v2, v213
	ds_add_u32 v3, v213
	ds_add_u32 v67, v213
	v_cmp_eq_u32_e32 vcc, 0, v37
	v_cmp_eq_u32_e64 s[98:99], 0, v40
	v_cmp_eq_u32_e64 s[100:101], 0, v39
	v_lshrrev_b32_e32 v2, 20, v37
	v_lshrrev_b32_e32 v3, 20, v40
	v_lshrrev_b32_e32 v67, 20, v39
	v_cndmask_b32_e32 v2, v2, v221, vcc
	v_cndmask_b32_e64 v3, v3, v221, s[98:99]
	v_cndmask_b32_e64 v67, v67, v221, s[100:101]
	v_lshl_add_u32 v2, v2, 2, s34
	v_lshl_add_u32 v3, v3, 2, s34
	v_lshl_add_u32 v67, v67, 2, s34
	ds_add_u32 v2, v213
	ds_add_u32 v3, v213
	ds_add_u32 v67, v213
	v_cmp_eq_u32_e32 vcc, 0, v42
	v_cmp_eq_u32_e64 s[98:99], 0, v41
	v_lshrrev_b32_e32 v2, 20, v42
	v_lshrrev_b32_e32 v3, 20, v41
	v_cndmask_b32_e32 v2, v2, v221, vcc
	v_cndmask_b32_e64 v3, v3, v221, s[98:99]
	v_lshl_add_u32 v2, v2, 2, s34
	v_lshl_add_u32 v3, v3, 2, s34
	ds_add_u32 v2, v213
	ds_add_u32 v3, v213
	v_cndmask_b32_e64 v2, 0, 1, s[10:11]
	v_cmp_ne_u32_e64 s[8:9], 1, v2
	s_andn2_b64 vcc, exec, s[10:11]
	s_cbranch_vccnz .LBB0_488
.LBB0_518:
	s_waitcnt lgkmcnt(14)
	v_cmp_eq_u32_e32 vcc, 0, v44
	v_cmp_eq_u32_e64 s[98:99], 0, v43
	v_cmp_eq_u32_e64 s[100:101], 0, v46
	v_lshrrev_b32_e32 v2, 20, v44
	v_lshrrev_b32_e32 v3, 20, v43
	v_lshrrev_b32_e32 v67, 20, v46
	v_cndmask_b32_e32 v2, v2, v221, vcc
	v_cndmask_b32_e64 v3, v3, v221, s[98:99]
	v_cndmask_b32_e64 v67, v67, v221, s[100:101]
	v_lshl_add_u32 v2, v2, 2, s34
	v_lshl_add_u32 v3, v3, 2, s34
	v_lshl_add_u32 v67, v67, 2, s34
	ds_add_u32 v2, v213
	ds_add_u32 v3, v213
	ds_add_u32 v67, v213
	v_cmp_eq_u32_e32 vcc, 0, v45
	v_cmp_eq_u32_e64 s[98:99], 0, v48
	v_cmp_eq_u32_e64 s[100:101], 0, v47
	v_lshrrev_b32_e32 v2, 20, v45
	v_lshrrev_b32_e32 v3, 20, v48
	v_lshrrev_b32_e32 v67, 20, v47
	v_cndmask_b32_e32 v2, v2, v221, vcc
	v_cndmask_b32_e64 v3, v3, v221, s[98:99]
	v_cndmask_b32_e64 v67, v67, v221, s[100:101]
	v_lshl_add_u32 v2, v2, 2, s34
	v_lshl_add_u32 v3, v3, 2, s34
	v_lshl_add_u32 v67, v67, 2, s34
	ds_add_u32 v2, v213
	ds_add_u32 v3, v213
	ds_add_u32 v67, v213
	v_cmp_eq_u32_e32 vcc, 0, v50
	v_cmp_eq_u32_e64 s[98:99], 0, v49
	v_lshrrev_b32_e32 v2, 20, v50
	v_lshrrev_b32_e32 v3, 20, v49
	v_cndmask_b32_e32 v2, v2, v221, vcc
	v_cndmask_b32_e64 v3, v3, v221, s[98:99]
	v_lshl_add_u32 v2, v2, 2, s34
	v_lshl_add_u32 v3, v3, 2, s34
	ds_add_u32 v2, v213
	ds_add_u32 v3, v213
	v_cndmask_b32_e64 v2, 0, 1, s[12:13]
	v_cmp_ne_u32_e64 s[10:11], 1, v2
	s_andn2_b64 vcc, exec, s[12:13]
	s_cbranch_vccnz .LBB0_489
.LBB0_519:
	s_waitcnt lgkmcnt(14)
	v_cmp_eq_u32_e32 vcc, 0, v52
	v_cmp_eq_u32_e64 s[98:99], 0, v51
	v_cmp_eq_u32_e64 s[100:101], 0, v54
	v_lshrrev_b32_e32 v2, 20, v52
	v_lshrrev_b32_e32 v3, 20, v51
	v_lshrrev_b32_e32 v67, 20, v54
	v_cndmask_b32_e32 v2, v2, v221, vcc
	v_cndmask_b32_e64 v3, v3, v221, s[98:99]
	v_cndmask_b32_e64 v67, v67, v221, s[100:101]
	v_lshl_add_u32 v2, v2, 2, s34
	v_lshl_add_u32 v3, v3, 2, s34
	v_lshl_add_u32 v67, v67, 2, s34
	ds_add_u32 v2, v213
	ds_add_u32 v3, v213
	ds_add_u32 v67, v213
	v_cmp_eq_u32_e32 vcc, 0, v53
	v_cmp_eq_u32_e64 s[98:99], 0, v56
	v_cmp_eq_u32_e64 s[100:101], 0, v55
	v_lshrrev_b32_e32 v2, 20, v53
	v_lshrrev_b32_e32 v3, 20, v56
	v_lshrrev_b32_e32 v67, 20, v55
	v_cndmask_b32_e32 v2, v2, v221, vcc
	v_cndmask_b32_e64 v3, v3, v221, s[98:99]
	v_cndmask_b32_e64 v67, v67, v221, s[100:101]
	v_lshl_add_u32 v2, v2, 2, s34
	v_lshl_add_u32 v3, v3, 2, s34
	v_lshl_add_u32 v67, v67, 2, s34
	ds_add_u32 v2, v213
	ds_add_u32 v3, v213
	ds_add_u32 v67, v213
	v_cmp_eq_u32_e32 vcc, 0, v58
	v_cmp_eq_u32_e64 s[98:99], 0, v57
	v_lshrrev_b32_e32 v2, 20, v58
	v_lshrrev_b32_e32 v3, 20, v57
	v_cndmask_b32_e32 v2, v2, v221, vcc
	v_cndmask_b32_e64 v3, v3, v221, s[98:99]
	v_lshl_add_u32 v2, v2, 2, s34
	v_lshl_add_u32 v3, v3, 2, s34
	ds_add_u32 v2, v213
	ds_add_u32 v3, v213
	v_cndmask_b32_e64 v2, 0, 1, s[16:17]
	v_cmp_ne_u32_e64 s[12:13], 1, v2
	s_andn2_b64 vcc, exec, s[16:17]
	s_cbranch_vccz .LBB0_490
	s_branch .LBB0_491
